# layer-1 FFN1 and W_in weight conversion (6144 of 12416 transpose items) in layer-0 FFN2up idle slots; layer-1 prologue skips them
# speedup vs baseline: 1.0020x; 1.0020x over previous
; __device__ __forceinline__ void prologue(Frame& F, const Args& A, int l) {
;     ...
;     for (int it = gw; it < NITEMS; it += NGW) {
;         int r = it, si, sci = -1, K = DM, N = FFH, rs = 128, off = 0, nblk = 32; size_t so = oFF, dsto;
;         if (r < 6 * 1408) { const int w = r / 1408; r -= w * 1408; const int second = w >= 3, t = w % 3;
.LBB0_11:
	v_readlane_b32 vcc_lo, v255, 18
	s_nop 1
	s_cmp_eq_u32 vcc_lo, 0
	s_cbranch_scc1 .Lpro_keep
	s_cmpk_lt_i32 s13, 0x2100
	s_cbranch_scc1 .Lpro_keep
	s_cmpk_gt_i32 s13, 0x287f
	s_cbranch_scc1 .Lpro_keep
	s_add_i32 s13, s13, s12
	s_cmpk_gt_i32 s13, 0x307f
	s_cbranch_scc1 .LBB0_49
	s_branch .LBB0_11

; __device__ __forceinline__ void prologue(Frame& F, const Args& A, int l) {
;     ...
;     const int gw = F.vcu * NWAVES + F.wave, NGW = F.G * NWAVES;
;     unsigned char* ws = F.ws;
;     const size_t oFF = (size_t)l * DM * FFH, oDD = (size_t)l * DM * DM;
;     constexpr int I_GU = 16 * 88, I_DN = 44 * 32, I_IN = 16 * 120, I_SQ = 16 * 32;
;     constexpr int NITEMS = 6 * 1408 + I_IN + 4 * I_SQ;
;     for (int it = gw; it < NITEMS; it += NGW) {
.LBB0_1228:
	v_readlane_b32 vcc_lo, v255, 18
	s_nop 1
	s_cmp_lg_u32 vcc_lo, 0
	s_cbranch_scc1 .Lpi_exit
	s_cmpk_lt_u32 s83, 0x80
	s_cbranch_scc1 .Lpi_exit
	v_readlane_b32 s90, v255, 24
	v_readlane_b32 s91, v255, 25
	s_nop 1
	s_mov_b32 vcc_lo, 0
	s_nop 0
	v_writelane_b32 v255, vcc_lo, 63
	s_movk_i32 vcc_lo, 0x107f
	s_nop 0
	v_writelane_b32 v255, vcc_lo, 62

; __device__ __forceinline__ unsigned cvt_pk_bf16(float lo, float hi) { const f32x2cv v = {lo, hi}; const bf16x2cv b = __builtin_convertvector(v, bf16x2cv); return __builtin_bit_cast(unsigned, b); }
; #define LAS __attribute__((address_space(3)))
; #define LDS_WAIT() asm volatile("s_waitcnt lgkmcnt(0)" ::: "memory")
; __device__ __forceinline__ void transpose_item(const float* W, int K, int N, bf16* WT, int rs, int off, const float* sc, LAS float* scr, int item, int nblk, int lane, int swp) {
;     ...
;     for (int j = 0; j < 4; ++j) { const int nn = (lane >> 3) + 8 * j; const LAS float* s = scr + (8 * c) * 33 + nn;
;         v4u o; o.x = cvt_pk_bf16(s[0 * 33] * s0[0], s[1 * 33] * s0[1]); o.y = cvt_pk_bf16(s[2 * 33] * s0[2], s[3 * 33] * s0[3]); o.z = cvt_pk_bf16(s[4 * 33] * s1[0], s[5 * 33] * s1[1]); o.w = cvt_pk_bf16(s[6 * 33] * s1[2], s[7 * 33] * s1[3]);
;         const int ng = n0 + nn, t256 = ng >> 8, ts256 = (t256 == 2) ? 7 : (t256 == 7) ? 2 : t256, dr = swp ? ts256 * 256 + (ng & 255) : (ng / 128) * rs + off + (ng % 128);
;         *(v4u*)(WT + (size_t)dr * K + k0 + 8 * c) = o; }
;     LDS_WAIT(); asm volatile("" ::: "memory");
; __device__ __forceinline__ void prologue(Frame& F, const Args& A, int l) {
;     ...
;     const int gw = F.vcu * NWAVES + F.wave, NGW = F.G * NWAVES;
;     unsigned char* ws = F.ws;
;     const size_t oFF = (size_t)l * DM * FFH, oDD = (size_t)l * DM * DM;
;     constexpr int I_GU = 16 * 88, I_DN = 44 * 32, I_IN = 16 * 120, I_SQ = 16 * 32;
;     constexpr int NITEMS = 6 * 1408 + I_IN + 4 * I_SQ;
;     for (int it = gw; it < NITEMS; it += NGW) {
;         int r = it, si, sci = -1, K = DM, N = FFH, rs = 128, off = 0, nblk = 32; size_t so = oFF, dsto;
.Lpi_b8:
	s_ashr_i32 s35, s4, 6
	s_lshl_b32 s36, s1, 3
	s_mov_b32 s4, 1
	s_add_i32 s34, s83, 0xffffff80
	s_lshl_b32 s34, s34, 3
	s_add_i32 s34, s34, s35
	s_movk_i32 s12, 0x400
	s_lshl_b32 s4, s4, 10
	v_and_b32_e32 v20, 63, v9
	v_readlane_b32 vcc_lo, v255, 62
	s_nop 1
	s_cmp_gt_i32 s34, vcc_lo
	v_readlane_b32 s5, v255, 19
	s_cbranch_scc1 .Lpi_done1
	s_lshl_b32 s8, s35, 14
	s_mul_i32 s68, s4, 0xb00
	s_add_i32 s2, s2, s8
	v_and_b32_e32 v21, 31, v9
	v_lshrrev_b32_e32 v22, 5, v20
	v_and_b32_e32 v2, 7, v9
	v_lshrrev_b32_e32 v23, 3, v20
	s_mov_b32 s5, s69
	s_mov_b64 s[6:7], s[68:69]
	s_mul_i32 s68, s4, 0xe08
	v_lshl_add_u32 v0, v21, 2, s2
	v_mul_u32_u24_e32 v1, 0x84, v22
	v_lshlrev_b32_e32 v8, 3, v2
	v_mul_u32_u24_e32 v2, 0x420, v2
	v_lshlrev_b32_e32 v3, 2, v23
	s_lshl_b64 s[14:15], s[4:5], 10
	s_mov_b64 s[16:17], s[68:69]
	v_add3_u32 v24, s2, v2, v3
	v_or_b32_e32 v25, 8, v23
	v_or_b32_e32 v26, 16, v23
	v_or_b32_e32 v27, 24, v23
	v_add_u32_e32 v28, v0, v1
	v_lshlrev_b32_e32 v192, 1, v8
	s_lshr_b32 s13, s12, 1
	s_add_i32 s13, s34, s13
	s_cmp_ge_i32 s13, s12
	s_cbranch_scc0 .Lpi_Lpro_rot_ok
	s_sub_i32 s13, s13, s12
.Lpi_Lpro_rot_ok:
	v_readlane_b32 vcc_lo, v255, 63
	s_nop 1
	s_add_i32 s13, s13, vcc_lo
	s_branch .Lpi_b11
.Lpi_b10:
	s_waitcnt lgkmcnt(0)
	v_pk_mul_f32 v[4:5], v[4:5], v[18:19]
	v_pk_mul_f32 v[6:7], v[6:7], v[16:17]
	v_pk_mul_f32 v[0:1], v[0:1], v[14:15]
	v_cvt_pk_bf16_f32 v4, v4, v5
	v_cvt_pk_bf16_f32 v5, v6, v7
	v_cvt_pk_bf16_f32 v6, v0, v1
	v_pk_mul_f32 v[0:1], v[2:3], v[12:13]
	s_add_i32 s13, s13, s12
	v_cvt_pk_bf16_f32 v7, v0, v1
	v_mad_i64_i32 v[0:1], s[18:19], s18, v29, 0
	v_lshl_add_u64 v[0:1], v[0:1], 1, v[10:11]
	flat_store_dwordx4 v[0:1], v[4:7]
	s_waitcnt lgkmcnt(0)
	v_readlane_b32 vcc_lo, v255, 62
	s_nop 1
	s_cmp_gt_i32 s13, vcc_lo
	s_cbranch_scc1 .Lpi_done1

; __device__ __forceinline__ void prologue(Frame& F, const Args& A, int l) {
;     ...
;     for (int it = gw; it < NITEMS; it += NGW) {
.Lpi_done1:
	v_readlane_b32 vcc_lo, v255, 63
	s_nop 1
	s_cmp_lg_u32 vcc_lo, 0
	s_cbranch_scc1 .Lpi_exit
	s_movk_i32 vcc_lo, 0x2100
	s_nop 0
	v_writelane_b32 v255, vcc_lo, 63
	s_movk_i32 vcc_lo, 0x287f
	s_nop 0
	v_writelane_b32 v255, vcc_lo, 62
	s_branch .Lpi_again
